# code placement: pad (branched-over nops) so both attention key-loop heads sit at the byte alignment that measured best
# speedup vs baseline: 1.0029x; 1.0029x over previous
; __device__ __forceinline__ unsigned pk2(float lo, float hi) { unsigned r; asm("v_cvt_pk_bf16_f32 %0, %1, %2" : "=v"(r) : "v"(lo), "v"(hi)); return r; }
; __device__ __forceinline__ void attn_block(KP p, LAS unsigned char* lds, int bh, int q0) {
;     ...
;     const int b = bh >> 2, hd = bh & 3; const size_t grow = (size_t)b * SEQ + qrow;
;     if (lh == 0) ((float*)(ws + OFF_SSQM))[grow * 4 + hd] = ss;
;     bf16_t* od = (bf16_t*)(ws + OFF_MIX) + grow * DM + 256 + 64 * hd + 4 * lh;
; #pragma unroll
;     for (int g = 0; g < 4; ++g) {
;         u32x2 a, c; a.x = pk2(o0[4 * g], o0[4 * g + 1]); a.y = pk2(o0[4 * g + 2], o0[4 * g + 3]); c.x = pk2(o1[4 * g], o1[4 * g + 1]); c.y = pk2(o1[4 * g + 2], o1[4 * g + 3]);
;         *(u32x2*)(od + 8 * g) = a; *(u32x2*)(od + 32 + 8 * g) = c;
;     }
;     __syncthreads();
.LBB0_240:
	s_or_b64 exec, exec, s[6:7]
	v_lshlrev_b64 v[34:35], 11, v[34:35]
	v_lshl_add_u64 v[34:35], s[94:95], 0, v[34:35]
	s_lshl_b32 s18, s8, 1
	v_lshl_add_u64 v[34:35], v[34:35], 0, s[18:19]
	v_lshlrev_b32_e32 v0, 1, v145
	v_lshl_add_u64 v[34:35], v[34:35], 0, v[0:1]
	v_cvt_pk_bf16_f32 v2, v2, v3
	v_cvt_pk_bf16_f32 v3, v4, v5
	v_add_co_u32_e32 v4, vcc, s86, v34
	s_mov_b64 s[6:7], 0x110b0200
	v_cvt_pk_bf16_f32 v18, v18, v19
	v_cvt_pk_bf16_f32 v19, v20, v21
	s_nop 0
	v_addc_co_u32_e32 v5, vcc, 0, v35, vcc
	s_waitcnt lgkmcnt(0)
	v_lshl_add_u64 v[36:37], v[34:35], 0, s[6:7]
	global_store_dwordx2 v[4:5], v[18:19], off offset:512
	global_store_dwordx2 v[36:37], v[2:3], off offset:64
	v_cvt_pk_bf16_f32 v2, v22, v23
	v_cvt_pk_bf16_f32 v3, v24, v25
	v_cvt_pk_bf16_f32 v4, v6, v7
	v_cvt_pk_bf16_f32 v5, v8, v9
	global_store_dwordx2 v[36:37], v[2:3], off offset:16
	global_store_dwordx2 v[36:37], v[4:5], off offset:80
	v_cvt_pk_bf16_f32 v2, v26, v27
	v_cvt_pk_bf16_f32 v3, v28, v29
	s_add_i32 s54, s54, s52
	v_cvt_pk_bf16_f32 v4, v10, v11
	v_cvt_pk_bf16_f32 v5, v12, v13
	global_store_dwordx2 v[36:37], v[2:3], off offset:32
	global_store_dwordx2 v[36:37], v[4:5], off offset:96
	v_cvt_pk_bf16_f32 v2, v30, v31
	v_cvt_pk_bf16_f32 v3, v32, v33
	s_cmpk_gt_i32 s54, 0xff
	v_cvt_pk_bf16_f32 v4, v14, v15
	v_cvt_pk_bf16_f32 v5, v16, v17
	global_store_dwordx2 v[36:37], v[2:3], off offset:48
	global_store_dwordx2 v[36:37], v[4:5], off offset:112
	s_branch .Lpad_a
	s_nop 0
	s_nop 0
	s_nop 0
	s_nop 0
	s_nop 0
	s_nop 0
	s_nop 0
	s_nop 0
	s_nop 0
	s_nop 0
	s_nop 0
	s_nop 0
	s_nop 0
	s_nop 0
	s_nop 0
	s_nop 0
	s_nop 0
	s_nop 0
	s_nop 0
	s_nop 0
	s_nop 0
	s_nop 0
	s_nop 0
	s_nop 0
.Lpad_a:
	s_barrier
	s_cbranch_scc1 .LBB0_277

; #define LAS __attribute__((address_space(3)))
; __device__ __forceinline__ unsigned pk2(float lo, float hi) { unsigned r; asm("v_cvt_pk_bf16_f32 %0, %1, %2" : "=v"(r) : "v"(lo), "v"(hi)); return r; }
; __device__ __forceinline__ void attn_block(KP p, LAS unsigned char* lds, int bh, int q0) {
;     int tid = threadIdx.x; asm volatile("" : "+v"(tid));
;     const int lane = tid & 63, w = __builtin_amdgcn_readfirstlane(tid >> 6), lr = lane & 31, lh = lane >> 5;
;     unsigned char* ws = p->ws;
;     const bf16_t* Qg = (const bf16_t*)(ws + OFF_Q) + (size_t)bh * SEQ * 96;
;     const bf16_t* Kg = (const bf16_t*)(ws + OFF_K) + (size_t)bh * SEQ * 96;
;     const bf16_t* Vg = (const bf16_t*)(ws + OFF_VT) + (size_t)bh * 64 * SEQ;
;     const int qrow = q0 + 32 * w + lr, wave_q0 = q0 + 32 * w;
;     bf16x8 qf[6];
; #pragma unroll
;     for (int ks = 0; ks < 6; ++ks) qf[ks] = *(const bf16x8*)(Qg + (size_t)qrow * 96 + 16 * ks + 8 * lh);
;     f32x16 o0, o1;
; #pragma unroll
;     for (int i = 0; i < 16; ++i) { o0[i] = 0.f; o1[i] = 0.f; }
;     float mrun = -1e30f, lrun = 0.f;
;     const int nst = (q0 + 256) / 128;
;     u32x4 rk[3], rv[2];
; #pragma unroll
;     for (int i = 0; i < 3; ++i) { const int q = tid + 512 * i; rk[i] = *(const u32x4*)(Kg + (size_t)(q / 12) * 96 + 8 * (q % 12)); }
; #pragma unroll
;     for (int i = 0; i < 2; ++i) { const int q = tid + 512 * i; rv[i] = *(const u32x4*)(Vg + (size_t)(q >> 4) * SEQ + 8 * (q & 15)); }
;     ...
;     const int b = bh >> 2, hd = bh & 3; const size_t grow = (size_t)b * SEQ + qrow;
;     if (lh == 0) ((float*)(ws + OFF_SSQM))[grow * 4 + hd] = ss;
;     bf16_t* od = (bf16_t*)(ws + OFF_MIX) + grow * DM + 256 + 64 * hd + 4 * lh;
; #pragma unroll
;     for (int g = 0; g < 4; ++g) {
;         u32x2 a, c; a.x = pk2(o0[4 * g], o0[4 * g + 1]); a.y = pk2(o0[4 * g + 2], o0[4 * g + 3]); c.x = pk2(o1[4 * g], o1[4 * g + 1]); c.y = pk2(o1[4 * g + 2], o1[4 * g + 3]);
;         *(u32x2*)(od + 8 * g) = a; *(u32x2*)(od + 32 + 8 * g) = c;
;     }
;     __syncthreads();
.LBB0_259:
	s_or_b64 exec, exec, s[6:7]
	v_lshlrev_b64 v[34:35], 11, v[34:35]
	v_lshl_add_u64 v[34:35], s[94:95], 0, v[34:35]
	s_lshl_b32 s18, s83, 7
	v_lshl_add_u64 v[34:35], v[34:35], 0, s[18:19]
	v_lshlrev_b32_e32 v0, 1, v145
	v_lshl_add_u64 v[34:35], v[34:35], 0, v[0:1]
	v_cvt_pk_bf16_f32 v2, v2, v3
	v_cvt_pk_bf16_f32 v3, v4, v5
	v_add_co_u32_e32 v4, vcc, s86, v34
	s_mov_b64 s[6:7], 0x110b0200
	v_cvt_pk_bf16_f32 v18, v18, v19
	v_cvt_pk_bf16_f32 v19, v20, v21
	s_nop 0
	v_addc_co_u32_e32 v5, vcc, 0, v35, vcc
	s_waitcnt lgkmcnt(0)
	v_lshl_add_u64 v[36:37], v[34:35], 0, s[6:7]
	global_store_dwordx2 v[4:5], v[18:19], off offset:512
	global_store_dwordx2 v[36:37], v[2:3], off offset:64
	v_cvt_pk_bf16_f32 v2, v22, v23
	v_cvt_pk_bf16_f32 v3, v24, v25
	v_cvt_pk_bf16_f32 v4, v6, v7
	v_cvt_pk_bf16_f32 v5, v8, v9
	global_store_dwordx2 v[36:37], v[2:3], off offset:16
	global_store_dwordx2 v[36:37], v[4:5], off offset:80
	v_cvt_pk_bf16_f32 v2, v26, v27
	v_cvt_pk_bf16_f32 v3, v28, v29
	v_cvt_pk_bf16_f32 v4, v10, v11
	v_cvt_pk_bf16_f32 v5, v12, v13
	global_store_dwordx2 v[36:37], v[2:3], off offset:32
	global_store_dwordx2 v[36:37], v[4:5], off offset:96
	v_cvt_pk_bf16_f32 v2, v30, v31
	v_cvt_pk_bf16_f32 v3, v32, v33
	v_mov_b32_e32 v22, v167
	v_cvt_pk_bf16_f32 v4, v14, v15
	v_cvt_pk_bf16_f32 v5, v16, v17
	global_store_dwordx2 v[36:37], v[2:3], off offset:48
	global_store_dwordx2 v[36:37], v[4:5], off offset:112
	s_branch .Lpad_b
	s_nop 0
	s_nop 0
	s_nop 0
.Lpad_b:
	s_barrier
	s_xor_b32 s18, s55, 0xf00
	v_readfirstlane_b32 s6, v22
	s_ashr_i32 s6, s6, 1
	s_andn2_b32 s6, s6, 31
	v_and_b32_e32 v23, 31, v22
	s_add_i32 s6, s6, s18
	v_bfe_u32 v157, v22, 5, 1
	v_or_b32_e32 v142, s6, v23
	v_mov_b64_e32 v[2:3], s[10:11]
	v_mad_i64_i32 v[2:3], s[10:11], v142, s57, v[2:3]
	v_lshlrev_b32_e32 v144, 4, v157
	v_mov_b32_e32 v145, v1
	v_lshl_add_u64 v[2:3], v[2:3], 0, v[144:145]
	v_mul_hi_i32 v0, v22, s63
	global_load_dwordx4 v[66:69], v[2:3], off
	global_load_dwordx4 v[70:73], v[2:3], off offset:32
	global_load_dwordx4 v[74:77], v[2:3], off offset:64
	global_load_dwordx4 v[78:81], v[2:3], off offset:96
	global_load_dwordx4 v[82:85], v[2:3], off offset:128
	global_load_dwordx4 v[86:89], v[2:3], off offset:160
	v_lshrrev_b32_e32 v2, 31, v0
	v_ashrrev_i32_e32 v0, 1, v0
	v_add_u32_e32 v24, v0, v2
	v_mul_lo_u32 v0, v24, 12
	v_add_u32_e32 v14, 0x200, v22
	v_sub_u32_e32 v25, v22, v0
	v_mul_hi_i32 v0, v14, s63
	v_lshrrev_b32_e32 v4, 31, v0
	v_ashrrev_i32_e32 v0, 1, v0
	v_add_u32_e32 v26, v0, v4
	v_mul_lo_u32 v0, v26, 12
	v_sub_u32_e32 v27, v14, v0
	v_add_u32_e32 v0, 0x400, v22
	v_mul_hi_i32 v6, v0, s63
	v_lshrrev_b32_e32 v7, 31, v6
	v_ashrrev_i32_e32 v6, 1, v6
	v_add_u32_e32 v28, v6, v7
	v_mul_lo_u32 v6, v28, 12
	v_sub_u32_e32 v29, v0, v6
	v_lshlrev_b32_e32 v0, 3, v22
	v_and_b32_e32 v158, 0x78, v0
	v_ashrrev_i32_e32 v10, 4, v22
	v_ashrrev_i32_e32 v14, 4, v14
	v_lshlrev_b32_e32 v0, 1, v158
	v_ashrrev_i32_e32 v11, 31, v10
	v_ashrrev_i32_e32 v15, 31, v14
	v_lshl_add_u64 v[8:9], s[12:13], 0, v[0:1]
	v_lshlrev_b64 v[12:13], 13, v[10:11]
	v_lshlrev_b64 v[16:17], 13, v[14:15]
	v_lshlrev_b32_e32 v2, 3, v25
	v_lshlrev_b32_e32 v6, 3, v29
	v_lshl_add_u64 v[18:19], v[8:9], 0, v[16:17]
	v_lshl_add_u64 v[8:9], v[8:9], 0, v[12:13]
	v_ashrrev_i32_e32 v3, 31, v2
	v_lshlrev_b32_e32 v4, 3, v27
	v_ashrrev_i32_e32 v7, 31, v6
	global_load_dwordx4 v[94:97], v[18:19], off
	global_load_dwordx4 v[90:93], v[8:9], off
	v_mov_b64_e32 v[8:9], s[8:9]
	v_ashrrev_i32_e32 v5, 31, v4
	v_mad_i64_i32 v[18:19], s[8:9], v28, s57, v[8:9]
	v_lshlrev_b64 v[6:7], 1, v[6:7]
	v_mad_i64_i32 v[20:21], s[8:9], v26, s57, v[8:9]
	v_mad_i64_i32 v[8:9], s[8:9], v24, s57, v[8:9]
	v_lshlrev_b64 v[2:3], 1, v[2:3]
	v_lshl_add_u64 v[18:19], v[18:19], 0, v[6:7]
	v_lshlrev_b64 v[4:5], 1, v[4:5]
	v_lshl_add_u64 v[8:9], v[8:9], 0, v[2:3]
	v_lshl_add_u64 v[20:21], v[20:21], 0, v[4:5]
	global_load_dwordx4 v[102:105], v[18:19], off
	global_load_dwordx4 v[98:101], v[20:21], off
	global_load_dwordx4 v[106:109], v[8:9], off
	v_and_b32_e32 v0, 15, v22
	v_lshl_add_u64 v[8:9], s[24:25], 0, v[16:17]
	v_lshlrev_b32_e32 v0, 4, v0
	v_lshl_add_u64 v[146:147], v[8:9], 0, v[0:1]
	v_lshl_add_u64 v[8:9], s[24:25], 0, v[12:13]
	v_lshl_add_u64 v[148:149], v[8:9], 0, v[0:1]
	v_mov_b64_e32 v[8:9], s[36:37]
	v_mul_lo_u32 v173, v10, s64
	v_mad_i64_i32 v[10:11], s[12:13], v28, s57, v[8:9]
	v_lshl_add_u64 v[150:151], v[10:11], 0, v[6:7]
	v_mad_i64_i32 v[6:7], s[12:13], v26, s57, v[8:9]
	v_mul_lo_u32 v174, v14, s64
	v_lshl_add_u64 v[152:153], v[6:7], 0, v[4:5]
	v_mad_i64_i32 v[4:5], s[12:13], v24, s57, v[8:9]
	v_mov_b32_e32 v14, v1
	v_mov_b32_e32 v15, v1
	v_mul_u32_u24_e32 v160, 0xd0, v23
	v_mul_u32_u24_e32 v161, 0x110, v23
	v_mul_lo_u32 v166, v24, s58
	v_lshlrev_b32_e32 v168, 4, v25
	v_mul_lo_u32 v169, v26, s58
	v_lshlrev_b32_e32 v170, 4, v27
	v_mul_lo_u32 v171, v28, s58
	v_lshlrev_b32_e32 v172, 4, v29
	v_lshl_add_u64 v[154:155], v[4:5], 0, v[2:3]
	v_mov_b32_e32 v0, v1
	v_mov_b32_e32 v2, v1
	v_mov_b32_e32 v3, v1
	v_mov_b32_e32 v4, v1
	v_mov_b32_e32 v5, v1
	v_mov_b32_e32 v6, v1
	v_mov_b32_e32 v7, v1
	v_mov_b32_e32 v8, v1
	v_mov_b32_e32 v9, v1
	v_mov_b32_e32 v10, v1
	v_mov_b32_e32 v11, v1
	v_mov_b32_e32 v12, v1
	v_mov_b32_e32 v13, v1
	v_mov_b64_e32 v[32:33], v[14:15]
	s_addk_i32 s18, 0x100
	v_mov_b64_e32 v[30:31], v[12:13]
	v_mov_b64_e32 v[28:29], v[10:11]
	v_mov_b64_e32 v[26:27], v[8:9]
	v_mov_b64_e32 v[24:25], v[6:7]
	v_mov_b64_e32 v[22:23], v[4:5]
	v_mov_b64_e32 v[20:21], v[2:3]
	v_mov_b64_e32 v[18:19], v[0:1]
	v_mov_b64_e32 v[16:17], v[14:15]
	s_lshl_b32 s8, s83, 6
	s_mov_b32 s7, 0
	v_ashrrev_i32_e32 v143, 31, v142
	v_lshlrev_b32_e32 v159, 3, v157
	s_lshr_b32 s9, s18, 7
	s_or_b32 s10, s6, 31
	v_lshlrev_b32_e32 v145, 2, v157
	v_mov_b32_e32 v175, 0
	v_mov_b32_e32 v176, 0xf149f2ca
	s_mov_b32 s11, 63
	v_mov_b64_e32 v[14:15], v[12:13]
	v_mov_b64_e32 v[12:13], v[10:11]
	v_mov_b64_e32 v[10:11], v[8:9]
	v_mov_b64_e32 v[8:9], v[6:7]
	v_mov_b64_e32 v[6:7], v[4:5]
	v_mov_b64_e32 v[4:5], v[2:3]
	v_mov_b64_e32 v[2:3], v[0:1]
	s_branch .LBB0_262
